# scan: LDS read burst + A prefetched two steps ahead (one wait per step); MLA softmax cross-half max via v_permlane32_swap instead of ds_bpermute
# speedup vs baseline: 1.0025x; 1.0025x over previous
; #define LAS __attribute__((address_space(3)))
; __device__ __forceinline__ float sum16(float x) { x += dpp_f<0xB1>(x); x += dpp_f<0x4E>(x); x += dpp_f<0x141>(x); x += dpp_f<0x140>(x); return x; }
; __device__ __forceinline__ void rwkv_scan_phase(LAS unsigned char* lds, const bf16_t* RKV, const float* DEC, const float* AF, const float* k_k, const float* k_a, const float* r_k, float* BON, float* Y, int bx, const int tid) {
;     ...
;     for (int c = 0; c < SEQ / SC_T; ++c) {
;         if (wid >= 4) { if (c + 1 < SEQ / SC_T) { SCAN_STORE((c + 1) & 1, c + 1); if (c + 2 < SEQ / SC_T) SCAN_LOAD(c + 2); } }
;         else {
;             const LAS unsigned char* base = lds + (c & 1) * SC_BUF + ks4; const LAS unsigned char* vbase = lds + (c & 1) * SC_BUF + 768 + rowi * 4;
;             f32x4 r4 = *(const LAS f32x4*)(base), w4 = *(const LAS f32x4*)(base + 256), k4 = *(const LAS f32x4*)(base + 512), a4 = *(const LAS f32x4*)(base + 1024), b4 = *(const LAS f32x4*)(base + 1280);
;             float vv = *(const LAS float*)(vbase); float ykeep = 0.f;
; #pragma unroll
;             for (int t = 0; t < SC_T; ++t) {
;                 f32x4 r4n = r4, w4n = w4, k4n = k4, a4n = a4, b4n = b4; float vvn = vv;
;                 if (t + 1 < SC_T) { const LAS unsigned char* p = base + (t + 1) * SC_TOK;
;                     r4n = *(const LAS f32x4*)(p); w4n = *(const LAS f32x4*)(p + 256); k4n = *(const LAS f32x4*)(p + 512); a4n = *(const LAS f32x4*)(p + 1024); b4n = *(const LAS f32x4*)(p + 1280);
;                     vvn = *(const LAS float*)(vbase + (t + 1) * SC_TOK); }
;                 const f32x2 a01 = {a4[0], a4[1]}, a23 = {a4[2], a4[3]}, w01 = {w4[0], w4[1]}, w23 = {w4[2], w4[3]}, b01 = {b4[0], b4[1]}, b23 = {b4[2], b4[3]}, k01 = {k4[0], k4[1]}, k23 = {k4[2], k4[3]}, r01 = {r4[0], r4[1]}, r23 = {r4[2], r4[3]};
;                 const f32x2 tsa = S01 * a01 + S23 * a23; const float sa = sum16(tsa[0] + tsa[1]);
;                 S01 = S01 * w01 + (b01 * sa + k01 * vv); S23 = S23 * w23 + (b23 * sa + k23 * vv);
;                 const f32x2 ty = S01 * r01 + S23 * r23; const float y = sum16(ty[0] + ty[1]);
;                 ykeep = ((lane & 15) == (t & 15)) ? y : ykeep;
;                 if ((t & 15) == 15) yp[(size_t)(c * SC_T + (t - 15) + (lane & 15)) * 2048] = ykeep;
;                 r4 = r4n; w4 = w4n; k4 = k4n; a4 = a4n; b4 = b4n; vv = vvn;
;             }
.LBB0_224:
	v_readlane_b32 s52, v255, 42
	v_readlane_b32 s53, v255, 43
	s_add_i32 s35, s21, -1
	s_mov_b64 s[76:77], -1
	s_and_b64 vcc, exec, s[52:53]
	s_cbranch_vccz .LBB0_226
	s_bitcmp1_b32 s35, 0
	s_cselect_b32 s52, 0xc000, 0
	v_add_u32_e32 v50, s52, v106
	v_add_u32_e32 v51, s52, v107
	ds_read_b128 v[0:3], v50 offset:1024
	ds_read_b128 v[8:11], v50 offset:512
	ds_read2st64_b32 v[40:41], v51 offset0:3 offset1:9
	ds_read_b128 v[4:7], v50 offset:256
	ds_read_b128 v[12:15], v50 offset:1280
	ds_read_b128 v[16:19], v50
	ds_read_b128 v[20:23], v50 offset:2560
	s_mov_b32 s40, 0xaaaaaaaa
	s_mov_b32 s41, 0xaaaaaaaa
	s_mov_b32 s46, 0xcccccccc
	s_mov_b32 s47, 0xcccccccc
	s_mov_b64 s[76:77], 0x20000
	s_waitcnt lgkmcnt(0)
	v_mul_f32_e32 v48, v94, v0
	v_fmac_f32_e32 v48, v95, v1
	v_fmac_f32_e32 v48, v96, v2
	v_fmac_f32_e32 v48, v97, v3
	ds_read_b128 v[0:3], v50 offset:4096
	ds_read_b128 v[28:31], v50 offset:2048
	ds_read_b128 v[24:27], v50 offset:1792
	ds_read_b128 v[32:35], v50 offset:2816
	ds_read_b128 v[36:39], v50 offset:1536
	v_add_f32_dpp v48, v48, v48 quad_perm:[1,0,3,2] row_mask:0xf bank_mask:0xf bound_ctrl:1
	v_mul_f32_e32 v44, v8, v40
	v_mul_f32_e32 v45, v9, v40
	v_mul_f32_e32 v46, v10, v40
	v_add_f32_dpp v48, v48, v48 quad_perm:[2,3,0,1] row_mask:0xf bank_mask:0xf bound_ctrl:1
	v_mul_f32_e32 v47, v11, v40
	v_fmac_f32_e32 v44, v94, v4
	v_fmac_f32_e32 v45, v95, v5
	v_add_f32_dpp v48, v48, v48 row_half_mirror row_mask:0xf bank_mask:0xf bound_ctrl:1
	v_fmac_f32_e32 v46, v96, v6
	v_fmac_f32_e32 v47, v97, v7
	v_add_f32_dpp v48, v48, v48 row_mirror row_mask:0xf bank_mask:0xf bound_ctrl:1
	v_fmac_f32_e32 v44, v12, v48
	v_fmac_f32_e32 v45, v13, v48
	v_fmac_f32_e32 v46, v14, v48
	v_fmac_f32_e32 v47, v15, v48
	v_mul_f32_e32 v48, v44, v20
	v_mul_f32_e32 v60, v44, v16
	v_fmac_f32_e32 v48, v45, v21
	v_fmac_f32_e32 v60, v45, v17
	v_fmac_f32_e32 v48, v46, v22
	v_fmac_f32_e32 v60, v46, v18
	v_fmac_f32_e32 v48, v47, v23
	v_fmac_f32_e32 v60, v47, v19
	ds_read_b128 v[20:23], v50 offset:5632
	ds_read_b128 v[8:11], v50 offset:3584
	ds_read2st64_b32 v[42:43], v51 offset0:15 offset1:21
	ds_read_b128 v[4:7], v50 offset:3328
	ds_read_b128 v[12:15], v50 offset:4352
	ds_read_b128 v[16:19], v50 offset:3072
	s_waitcnt lgkmcnt(6)
	v_add_f32_dpp v48, v48, v48 quad_perm:[1,0,3,2] row_mask:0xf bank_mask:0xf bound_ctrl:1
	v_mul_f32_e32 v94, v28, v41
	v_mul_f32_e32 v95, v29, v41
	v_mul_f32_e32 v96, v30, v41
	v_add_f32_dpp v48, v48, v48 quad_perm:[2,3,0,1] row_mask:0xf bank_mask:0xf bound_ctrl:1
	v_mul_f32_e32 v97, v31, v41
	v_fmac_f32_e32 v94, v44, v24
	v_fmac_f32_e32 v95, v45, v25
	v_add_f32_dpp v48, v48, v48 row_half_mirror row_mask:0xf bank_mask:0xf bound_ctrl:1
	v_fmac_f32_e32 v96, v46, v26
	v_fmac_f32_e32 v97, v47, v27
	v_add_f32_dpp v48, v48, v48 row_mirror row_mask:0xf bank_mask:0xf bound_ctrl:1
	v_fmac_f32_e32 v94, v32, v48
	v_fmac_f32_e32 v95, v33, v48
	v_fmac_f32_e32 v96, v34, v48
	v_fmac_f32_e32 v97, v35, v48
	v_mul_f32_e32 v48, v94, v0
	v_mul_f32_e32 v61, v94, v36
	v_fmac_f32_e32 v48, v95, v1
	v_fmac_f32_e32 v61, v95, v37
	v_fmac_f32_e32 v48, v96, v2
	v_fmac_f32_e32 v61, v96, v38
	v_fmac_f32_e32 v48, v97, v3
	v_fmac_f32_e32 v61, v97, v39
	ds_read_b128 v[0:3], v50 offset:7168
	ds_read_b128 v[28:31], v50 offset:5120
	ds_read_b128 v[24:27], v50 offset:4864
	ds_read_b128 v[32:35], v50 offset:5888
	ds_read_b128 v[36:39], v50 offset:4608
	s_waitcnt lgkmcnt(5)
	v_add_f32_dpp v48, v48, v48 quad_perm:[1,0,3,2] row_mask:0xf bank_mask:0xf bound_ctrl:1
	v_mul_f32_e32 v44, v8, v42
	v_mul_f32_e32 v45, v9, v42
	v_mul_f32_e32 v46, v10, v42
	v_add_f32_dpp v48, v48, v48 quad_perm:[2,3,0,1] row_mask:0xf bank_mask:0xf bound_ctrl:1
	v_mul_f32_e32 v47, v11, v42
	v_fmac_f32_e32 v44, v94, v4
	v_fmac_f32_e32 v45, v95, v5
	v_add_f32_dpp v48, v48, v48 row_half_mirror row_mask:0xf bank_mask:0xf bound_ctrl:1
	v_fmac_f32_e32 v46, v96, v6
	v_fmac_f32_e32 v47, v97, v7
	v_add_f32_dpp v48, v48, v48 row_mirror row_mask:0xf bank_mask:0xf bound_ctrl:1
	v_fmac_f32_e32 v44, v12, v48
	v_fmac_f32_e32 v45, v13, v48
	v_fmac_f32_e32 v46, v14, v48
	v_fmac_f32_e32 v47, v15, v48
	v_mul_f32_e32 v48, v44, v20
	v_mul_f32_e32 v62, v44, v16
	v_fmac_f32_e32 v48, v45, v21
	v_fmac_f32_e32 v62, v45, v17
	v_fmac_f32_e32 v48, v46, v22
	v_fmac_f32_e32 v62, v46, v18
	v_fmac_f32_e32 v48, v47, v23
	v_fmac_f32_e32 v62, v47, v19
	ds_read_b128 v[20:23], v50 offset:8704
	ds_read_b128 v[8:11], v50 offset:6656
	ds_read2st64_b32 v[40:41], v51 offset0:27 offset1:33
	ds_read_b128 v[4:7], v50 offset:6400
	ds_read_b128 v[12:15], v50 offset:7424
	ds_read_b128 v[16:19], v50 offset:6144
	s_waitcnt lgkmcnt(6)
	v_add_f32_dpp v48, v48, v48 quad_perm:[1,0,3,2] row_mask:0xf bank_mask:0xf bound_ctrl:1
	v_mul_f32_e32 v94, v28, v43
	v_mul_f32_e32 v95, v29, v43
	v_mul_f32_e32 v96, v30, v43
	v_add_f32_dpp v48, v48, v48 quad_perm:[2,3,0,1] row_mask:0xf bank_mask:0xf bound_ctrl:1
	v_mul_f32_e32 v97, v31, v43
	v_fmac_f32_e32 v94, v44, v24
	v_fmac_f32_e32 v95, v45, v25
	v_add_f32_dpp v48, v48, v48 row_half_mirror row_mask:0xf bank_mask:0xf bound_ctrl:1
	v_fmac_f32_e32 v96, v46, v26
	v_fmac_f32_e32 v97, v47, v27
	v_add_f32_dpp v48, v48, v48 row_mirror row_mask:0xf bank_mask:0xf bound_ctrl:1
	v_fmac_f32_e32 v94, v32, v48
	v_fmac_f32_e32 v95, v33, v48
	v_fmac_f32_e32 v96, v34, v48
	v_fmac_f32_e32 v97, v35, v48
	v_mul_f32_e32 v48, v94, v0
	v_mul_f32_e32 v63, v94, v36
	v_fmac_f32_e32 v48, v95, v1
	v_fmac_f32_e32 v63, v95, v37
	v_fmac_f32_e32 v48, v96, v2
	v_fmac_f32_e32 v63, v96, v38
	v_fmac_f32_e32 v48, v97, v3
	v_fmac_f32_e32 v63, v97, v39
	ds_read_b128 v[0:3], v50 offset:10240
	ds_read_b128 v[28:31], v50 offset:8192
	ds_read_b128 v[24:27], v50 offset:7936
	ds_read_b128 v[32:35], v50 offset:8960
	ds_read_b128 v[36:39], v50 offset:7680
	s_waitcnt lgkmcnt(5)
; #define LAS __attribute__((address_space(3)))
; __device__ __forceinline__ float sum16(float x) { x += dpp_f<0xB1>(x); x += dpp_f<0x4E>(x); x += dpp_f<0x141>(x); x += dpp_f<0x140>(x); return x; }
; __device__ __forceinline__ void rwkv_scan_phase(LAS unsigned char* lds, const bf16_t* RKV, const float* DEC, const float* AF, const float* k_k, const float* k_a, const float* r_k, float* BON, float* Y, int bx, const int tid) {
;     ...
;             for (int t = 0; t < SC_T; ++t) {
;                 f32x4 r4n = r4, w4n = w4, k4n = k4, a4n = a4, b4n = b4; float vvn = vv;
;                 if (t + 1 < SC_T) { const LAS unsigned char* p = base + (t + 1) * SC_TOK;
;                     r4n = *(const LAS f32x4*)(p); w4n = *(const LAS f32x4*)(p + 256); k4n = *(const LAS f32x4*)(p + 512); a4n = *(const LAS f32x4*)(p + 1024); b4n = *(const LAS f32x4*)(p + 1280);
;                     vvn = *(const LAS float*)(vbase + (t + 1) * SC_TOK); }
;                 const f32x2 a01 = {a4[0], a4[1]}, a23 = {a4[2], a4[3]}, w01 = {w4[0], w4[1]}, w23 = {w4[2], w4[3]}, b01 = {b4[0], b4[1]}, b23 = {b4[2], b4[3]}, k01 = {k4[0], k4[1]}, k23 = {k4[2], k4[3]}, r01 = {r4[0], r4[1]}, r23 = {r4[2], r4[3]};
;                 const f32x2 tsa = S01 * a01 + S23 * a23; const float sa = sum16(tsa[0] + tsa[1]);
;                 S01 = S01 * w01 + (b01 * sa + k01 * vv); S23 = S23 * w23 + (b23 * sa + k23 * vv);
;                 const f32x2 ty = S01 * r01 + S23 * r23; const float y = sum16(ty[0] + ty[1]);
;                 ykeep = ((lane & 15) == (t & 15)) ? y : ykeep;
;                 if ((t & 15) == 15) yp[(size_t)(c * SC_T + (t - 15) + (lane & 15)) * 2048] = ykeep;
;                 r4 = r4n; w4 = w4n; k4 = k4n; a4 = a4n; b4 = b4n; vv = vvn;
	v_add_f32_dpp v48, v48, v48 quad_perm:[1,0,3,2] row_mask:0xf bank_mask:0xf bound_ctrl:1
	v_mul_f32_e32 v44, v8, v40
	v_mul_f32_e32 v45, v9, v40
	v_mul_f32_e32 v46, v10, v40
	v_add_f32_dpp v48, v48, v48 quad_perm:[2,3,0,1] row_mask:0xf bank_mask:0xf bound_ctrl:1
	v_mul_f32_e32 v47, v11, v40
	v_fmac_f32_e32 v44, v94, v4
	v_fmac_f32_e32 v45, v95, v5
	v_add_f32_dpp v48, v48, v48 row_half_mirror row_mask:0xf bank_mask:0xf bound_ctrl:1
	v_fmac_f32_e32 v46, v96, v6
	v_fmac_f32_e32 v47, v97, v7
	v_add_f32_dpp v48, v48, v48 row_mirror row_mask:0xf bank_mask:0xf bound_ctrl:1
	v_fmac_f32_e32 v44, v12, v48
	v_fmac_f32_e32 v45, v13, v48
	v_fmac_f32_e32 v46, v14, v48
	v_fmac_f32_e32 v47, v15, v48
	v_mul_f32_e32 v48, v44, v20
	v_mul_f32_e32 v64, v44, v16
	v_fmac_f32_e32 v48, v45, v21
	v_fmac_f32_e32 v64, v45, v17
	v_fmac_f32_e32 v48, v46, v22
	v_fmac_f32_e32 v64, v46, v18
	v_fmac_f32_e32 v48, v47, v23
	v_fmac_f32_e32 v64, v47, v19
	ds_read_b128 v[20:23], v50 offset:11776
	ds_read_b128 v[8:11], v50 offset:9728
	ds_read2st64_b32 v[42:43], v51 offset0:39 offset1:45
	ds_read_b128 v[4:7], v50 offset:9472
	ds_read_b128 v[12:15], v50 offset:10496
	ds_read_b128 v[16:19], v50 offset:9216
	s_waitcnt lgkmcnt(6)
	v_add_f32_dpp v48, v48, v48 quad_perm:[1,0,3,2] row_mask:0xf bank_mask:0xf bound_ctrl:1
	v_mul_f32_e32 v94, v28, v41
	v_mul_f32_e32 v95, v29, v41
	v_mul_f32_e32 v96, v30, v41
	v_add_f32_dpp v48, v48, v48 quad_perm:[2,3,0,1] row_mask:0xf bank_mask:0xf bound_ctrl:1
	v_mul_f32_e32 v97, v31, v41
	v_fmac_f32_e32 v94, v44, v24
	v_fmac_f32_e32 v95, v45, v25
	v_add_f32_dpp v48, v48, v48 row_half_mirror row_mask:0xf bank_mask:0xf bound_ctrl:1
	v_fmac_f32_e32 v96, v46, v26
	v_fmac_f32_e32 v97, v47, v27
	v_add_f32_dpp v48, v48, v48 row_mirror row_mask:0xf bank_mask:0xf bound_ctrl:1
	v_fmac_f32_e32 v94, v32, v48
	v_fmac_f32_e32 v95, v33, v48
	v_fmac_f32_e32 v96, v34, v48
	v_fmac_f32_e32 v97, v35, v48
	v_mul_f32_e32 v48, v94, v0
	v_mul_f32_e32 v65, v94, v36
	v_fmac_f32_e32 v48, v95, v1
	v_fmac_f32_e32 v65, v95, v37
	v_fmac_f32_e32 v48, v96, v2
	v_fmac_f32_e32 v65, v96, v38
	v_fmac_f32_e32 v48, v97, v3
	v_fmac_f32_e32 v65, v97, v39
	ds_read_b128 v[0:3], v50 offset:13312
	ds_read_b128 v[28:31], v50 offset:11264
	ds_read_b128 v[24:27], v50 offset:11008
	ds_read_b128 v[32:35], v50 offset:12032
	ds_read_b128 v[36:39], v50 offset:10752
	s_waitcnt lgkmcnt(5)
	v_add_f32_dpp v48, v48, v48 quad_perm:[1,0,3,2] row_mask:0xf bank_mask:0xf bound_ctrl:1
	v_mul_f32_e32 v44, v8, v42
	v_mul_f32_e32 v45, v9, v42
	v_mul_f32_e32 v46, v10, v42
	v_add_f32_dpp v48, v48, v48 quad_perm:[2,3,0,1] row_mask:0xf bank_mask:0xf bound_ctrl:1
	v_mul_f32_e32 v47, v11, v42
	v_fmac_f32_e32 v44, v94, v4
	v_fmac_f32_e32 v45, v95, v5
	v_add_f32_dpp v48, v48, v48 row_half_mirror row_mask:0xf bank_mask:0xf bound_ctrl:1
	v_fmac_f32_e32 v46, v96, v6
	v_fmac_f32_e32 v47, v97, v7
	v_add_f32_dpp v48, v48, v48 row_mirror row_mask:0xf bank_mask:0xf bound_ctrl:1
	v_fmac_f32_e32 v44, v12, v48
	v_fmac_f32_e32 v45, v13, v48
	v_fmac_f32_e32 v46, v14, v48
	v_fmac_f32_e32 v47, v15, v48
	v_mul_f32_e32 v48, v44, v20
	v_mul_f32_e32 v66, v44, v16
	v_fmac_f32_e32 v48, v45, v21
	v_fmac_f32_e32 v66, v45, v17
	v_fmac_f32_e32 v48, v46, v22
	v_fmac_f32_e32 v66, v46, v18
	v_fmac_f32_e32 v48, v47, v23
	v_fmac_f32_e32 v66, v47, v19
	ds_read_b128 v[20:23], v50 offset:14848
	ds_read_b128 v[8:11], v50 offset:12800
	ds_read2st64_b32 v[40:41], v51 offset0:51 offset1:57
	ds_read_b128 v[4:7], v50 offset:12544
	ds_read_b128 v[12:15], v50 offset:13568
	ds_read_b128 v[16:19], v50 offset:12288
	s_waitcnt lgkmcnt(6)
	v_add_f32_dpp v48, v48, v48 quad_perm:[1,0,3,2] row_mask:0xf bank_mask:0xf bound_ctrl:1
	v_mul_f32_e32 v94, v28, v43
	v_mul_f32_e32 v95, v29, v43
	v_mul_f32_e32 v96, v30, v43
	v_add_f32_dpp v48, v48, v48 quad_perm:[2,3,0,1] row_mask:0xf bank_mask:0xf bound_ctrl:1
	v_mul_f32_e32 v97, v31, v43
	v_fmac_f32_e32 v94, v44, v24
	v_fmac_f32_e32 v95, v45, v25
	v_add_f32_dpp v48, v48, v48 row_half_mirror row_mask:0xf bank_mask:0xf bound_ctrl:1
	v_fmac_f32_e32 v96, v46, v26
	v_fmac_f32_e32 v97, v47, v27
	v_add_f32_dpp v48, v48, v48 row_mirror row_mask:0xf bank_mask:0xf bound_ctrl:1
	v_fmac_f32_e32 v94, v32, v48
	v_fmac_f32_e32 v95, v33, v48
	v_fmac_f32_e32 v96, v34, v48
	v_fmac_f32_e32 v97, v35, v48
	v_mul_f32_e32 v48, v94, v0
	v_mul_f32_e32 v67, v94, v36
	v_fmac_f32_e32 v48, v95, v1
	v_fmac_f32_e32 v67, v95, v37
	v_fmac_f32_e32 v48, v96, v2
	v_fmac_f32_e32 v67, v96, v38
	v_fmac_f32_e32 v48, v97, v3
	v_fmac_f32_e32 v67, v97, v39
	ds_read_b128 v[0:3], v50 offset:16384
	ds_read_b128 v[28:31], v50 offset:14336
	ds_read_b128 v[24:27], v50 offset:14080
	ds_read_b128 v[32:35], v50 offset:15104
	ds_read_b128 v[36:39], v50 offset:13824
	s_waitcnt lgkmcnt(5)
	v_add_f32_dpp v48, v48, v48 quad_perm:[1,0,3,2] row_mask:0xf bank_mask:0xf bound_ctrl:1
	v_mul_f32_e32 v44, v8, v40
	v_mul_f32_e32 v45, v9, v40
	v_mul_f32_e32 v46, v10, v40
	v_add_f32_dpp v48, v48, v48 quad_perm:[2,3,0,1] row_mask:0xf bank_mask:0xf bound_ctrl:1
	v_mul_f32_e32 v47, v11, v40
	v_fmac_f32_e32 v44, v94, v4
	v_fmac_f32_e32 v45, v95, v5
	v_add_f32_dpp v48, v48, v48 row_half_mirror row_mask:0xf bank_mask:0xf bound_ctrl:1
	v_fmac_f32_e32 v46, v96, v6
	v_fmac_f32_e32 v47, v97, v7
	v_add_f32_dpp v48, v48, v48 row_mirror row_mask:0xf bank_mask:0xf bound_ctrl:1
	v_fmac_f32_e32 v44, v12, v48
	v_fmac_f32_e32 v45, v13, v48
	v_fmac_f32_e32 v46, v14, v48
	v_fmac_f32_e32 v47, v15, v48
	v_mul_f32_e32 v48, v44, v20
	v_mul_f32_e32 v68, v44, v16
	v_fmac_f32_e32 v48, v45, v21
	v_fmac_f32_e32 v68, v45, v17
	v_fmac_f32_e32 v48, v46, v22
	v_fmac_f32_e32 v68, v46, v18
	v_fmac_f32_e32 v48, v47, v23
	v_fmac_f32_e32 v68, v47, v19
	ds_read_b128 v[20:23], v50 offset:17920
	ds_read_b128 v[8:11], v50 offset:15872
	ds_read2st64_b32 v[42:43], v51 offset0:63 offset1:69
	ds_read_b128 v[4:7], v50 offset:15616
	ds_read_b128 v[12:15], v50 offset:16640
	ds_read_b128 v[16:19], v50 offset:15360
	s_waitcnt lgkmcnt(6)
; #define LAS __attribute__((address_space(3)))
; __device__ __forceinline__ float sum16(float x) { x += dpp_f<0xB1>(x); x += dpp_f<0x4E>(x); x += dpp_f<0x141>(x); x += dpp_f<0x140>(x); return x; }
; __device__ __forceinline__ void rwkv_scan_phase(LAS unsigned char* lds, const bf16_t* RKV, const float* DEC, const float* AF, const float* k_k, const float* k_a, const float* r_k, float* BON, float* Y, int bx, const int tid) {
;     ...
;             for (int t = 0; t < SC_T; ++t) {
;                 f32x4 r4n = r4, w4n = w4, k4n = k4, a4n = a4, b4n = b4; float vvn = vv;
;                 if (t + 1 < SC_T) { const LAS unsigned char* p = base + (t + 1) * SC_TOK;
;                     r4n = *(const LAS f32x4*)(p); w4n = *(const LAS f32x4*)(p + 256); k4n = *(const LAS f32x4*)(p + 512); a4n = *(const LAS f32x4*)(p + 1024); b4n = *(const LAS f32x4*)(p + 1280);
;                     vvn = *(const LAS float*)(vbase + (t + 1) * SC_TOK); }
;                 const f32x2 a01 = {a4[0], a4[1]}, a23 = {a4[2], a4[3]}, w01 = {w4[0], w4[1]}, w23 = {w4[2], w4[3]}, b01 = {b4[0], b4[1]}, b23 = {b4[2], b4[3]}, k01 = {k4[0], k4[1]}, k23 = {k4[2], k4[3]}, r01 = {r4[0], r4[1]}, r23 = {r4[2], r4[3]};
;                 const f32x2 tsa = S01 * a01 + S23 * a23; const float sa = sum16(tsa[0] + tsa[1]);
;                 S01 = S01 * w01 + (b01 * sa + k01 * vv); S23 = S23 * w23 + (b23 * sa + k23 * vv);
;                 const f32x2 ty = S01 * r01 + S23 * r23; const float y = sum16(ty[0] + ty[1]);
;                 ykeep = ((lane & 15) == (t & 15)) ? y : ykeep;
;                 if ((t & 15) == 15) yp[(size_t)(c * SC_T + (t - 15) + (lane & 15)) * 2048] = ykeep;
;                 r4 = r4n; w4 = w4n; k4 = k4n; a4 = a4n; b4 = b4n; vv = vvn;
	v_add_f32_dpp v48, v48, v48 quad_perm:[1,0,3,2] row_mask:0xf bank_mask:0xf bound_ctrl:1
	v_mul_f32_e32 v94, v28, v41
	v_mul_f32_e32 v95, v29, v41
	v_mul_f32_e32 v96, v30, v41
	v_add_f32_dpp v48, v48, v48 quad_perm:[2,3,0,1] row_mask:0xf bank_mask:0xf bound_ctrl:1
	v_mul_f32_e32 v97, v31, v41
	v_fmac_f32_e32 v94, v44, v24
	v_fmac_f32_e32 v95, v45, v25
	v_add_f32_dpp v48, v48, v48 row_half_mirror row_mask:0xf bank_mask:0xf bound_ctrl:1
	v_fmac_f32_e32 v96, v46, v26
	v_fmac_f32_e32 v97, v47, v27
	v_add_f32_dpp v48, v48, v48 row_mirror row_mask:0xf bank_mask:0xf bound_ctrl:1
	v_fmac_f32_e32 v94, v32, v48
	v_fmac_f32_e32 v95, v33, v48
	v_fmac_f32_e32 v96, v34, v48
	v_fmac_f32_e32 v97, v35, v48
	v_mul_f32_e32 v48, v94, v0
	v_mul_f32_e32 v69, v94, v36
	v_fmac_f32_e32 v48, v95, v1
	v_fmac_f32_e32 v69, v95, v37
	v_fmac_f32_e32 v48, v96, v2
	v_fmac_f32_e32 v69, v96, v38
	v_fmac_f32_e32 v48, v97, v3
	v_fmac_f32_e32 v69, v97, v39
	ds_read_b128 v[0:3], v50 offset:19456
	ds_read_b128 v[28:31], v50 offset:17408
	ds_read_b128 v[24:27], v50 offset:17152
	ds_read_b128 v[32:35], v50 offset:18176
	ds_read_b128 v[36:39], v50 offset:16896
	s_waitcnt lgkmcnt(5)
	v_add_f32_dpp v48, v48, v48 quad_perm:[1,0,3,2] row_mask:0xf bank_mask:0xf bound_ctrl:1
	v_mul_f32_e32 v44, v8, v42
	v_mul_f32_e32 v45, v9, v42
	v_mul_f32_e32 v46, v10, v42
	v_add_f32_dpp v48, v48, v48 quad_perm:[2,3,0,1] row_mask:0xf bank_mask:0xf bound_ctrl:1
	v_mul_f32_e32 v47, v11, v42
	v_fmac_f32_e32 v44, v94, v4
	v_fmac_f32_e32 v45, v95, v5
	v_add_f32_dpp v48, v48, v48 row_half_mirror row_mask:0xf bank_mask:0xf bound_ctrl:1
	v_fmac_f32_e32 v46, v96, v6
	v_fmac_f32_e32 v47, v97, v7
	v_add_f32_dpp v48, v48, v48 row_mirror row_mask:0xf bank_mask:0xf bound_ctrl:1
	v_fmac_f32_e32 v44, v12, v48
	v_fmac_f32_e32 v45, v13, v48
	v_fmac_f32_e32 v46, v14, v48
	v_fmac_f32_e32 v47, v15, v48
	v_mul_f32_e32 v48, v44, v20
	v_mul_f32_e32 v70, v44, v16
	v_fmac_f32_e32 v48, v45, v21
	v_fmac_f32_e32 v70, v45, v17
	v_fmac_f32_e32 v48, v46, v22
	v_fmac_f32_e32 v70, v46, v18
	v_fmac_f32_e32 v48, v47, v23
	v_fmac_f32_e32 v70, v47, v19
	ds_read_b128 v[20:23], v50 offset:20992
	ds_read_b128 v[8:11], v50 offset:18944
	ds_read2st64_b32 v[40:41], v51 offset0:75 offset1:81
	ds_read_b128 v[4:7], v50 offset:18688
	ds_read_b128 v[12:15], v50 offset:19712
	ds_read_b128 v[16:19], v50 offset:18432
	s_waitcnt lgkmcnt(6)
	v_add_f32_dpp v48, v48, v48 quad_perm:[1,0,3,2] row_mask:0xf bank_mask:0xf bound_ctrl:1
	v_mul_f32_e32 v94, v28, v43
	v_mul_f32_e32 v95, v29, v43
	v_mul_f32_e32 v96, v30, v43
	v_add_f32_dpp v48, v48, v48 quad_perm:[2,3,0,1] row_mask:0xf bank_mask:0xf bound_ctrl:1
	v_mul_f32_e32 v97, v31, v43
	v_fmac_f32_e32 v94, v44, v24
	v_fmac_f32_e32 v95, v45, v25
	v_add_f32_dpp v48, v48, v48 row_half_mirror row_mask:0xf bank_mask:0xf bound_ctrl:1
	v_fmac_f32_e32 v96, v46, v26
	v_fmac_f32_e32 v97, v47, v27
	v_add_f32_dpp v48, v48, v48 row_mirror row_mask:0xf bank_mask:0xf bound_ctrl:1
	v_fmac_f32_e32 v94, v32, v48
	v_fmac_f32_e32 v95, v33, v48
	v_fmac_f32_e32 v96, v34, v48
	v_fmac_f32_e32 v97, v35, v48
	v_mul_f32_e32 v48, v94, v0
	v_mul_f32_e32 v71, v94, v36
	v_fmac_f32_e32 v48, v95, v1
	v_fmac_f32_e32 v71, v95, v37
	v_fmac_f32_e32 v48, v96, v2
	v_fmac_f32_e32 v71, v96, v38
	v_fmac_f32_e32 v48, v97, v3
	v_fmac_f32_e32 v71, v97, v39
	ds_read_b128 v[0:3], v50 offset:22528
	ds_read_b128 v[28:31], v50 offset:20480
	ds_read_b128 v[24:27], v50 offset:20224
	ds_read_b128 v[32:35], v50 offset:21248
	ds_read_b128 v[36:39], v50 offset:19968
	s_waitcnt lgkmcnt(5)
	v_add_f32_dpp v48, v48, v48 quad_perm:[1,0,3,2] row_mask:0xf bank_mask:0xf bound_ctrl:1
	v_mul_f32_e32 v44, v8, v40
	v_mul_f32_e32 v45, v9, v40
	v_mul_f32_e32 v46, v10, v40
	v_add_f32_dpp v48, v48, v48 quad_perm:[2,3,0,1] row_mask:0xf bank_mask:0xf bound_ctrl:1
	v_mul_f32_e32 v47, v11, v40
	v_fmac_f32_e32 v44, v94, v4
	v_fmac_f32_e32 v45, v95, v5
	v_add_f32_dpp v48, v48, v48 row_half_mirror row_mask:0xf bank_mask:0xf bound_ctrl:1
	v_fmac_f32_e32 v46, v96, v6
	v_fmac_f32_e32 v47, v97, v7
	v_add_f32_dpp v48, v48, v48 row_mirror row_mask:0xf bank_mask:0xf bound_ctrl:1
	v_fmac_f32_e32 v44, v12, v48
	v_fmac_f32_e32 v45, v13, v48
	v_fmac_f32_e32 v46, v14, v48
	v_fmac_f32_e32 v47, v15, v48
	v_mul_f32_e32 v48, v44, v20
	v_mul_f32_e32 v72, v44, v16
	v_fmac_f32_e32 v48, v45, v21
	v_fmac_f32_e32 v72, v45, v17
	v_fmac_f32_e32 v48, v46, v22
	v_fmac_f32_e32 v72, v46, v18
	v_fmac_f32_e32 v48, v47, v23
	v_fmac_f32_e32 v72, v47, v19
	ds_read_b128 v[20:23], v50 offset:24064
	ds_read_b128 v[8:11], v50 offset:22016
	ds_read2st64_b32 v[42:43], v51 offset0:87 offset1:93
	ds_read_b128 v[4:7], v50 offset:21760
	ds_read_b128 v[12:15], v50 offset:22784
	ds_read_b128 v[16:19], v50 offset:21504
	s_waitcnt lgkmcnt(6)
	v_add_f32_dpp v48, v48, v48 quad_perm:[1,0,3,2] row_mask:0xf bank_mask:0xf bound_ctrl:1
	v_mul_f32_e32 v94, v28, v41
	v_mul_f32_e32 v95, v29, v41
	v_mul_f32_e32 v96, v30, v41
	v_add_f32_dpp v48, v48, v48 quad_perm:[2,3,0,1] row_mask:0xf bank_mask:0xf bound_ctrl:1
	v_mul_f32_e32 v97, v31, v41
	v_fmac_f32_e32 v94, v44, v24
	v_fmac_f32_e32 v95, v45, v25
	v_add_f32_dpp v48, v48, v48 row_half_mirror row_mask:0xf bank_mask:0xf bound_ctrl:1
	v_fmac_f32_e32 v96, v46, v26
	v_fmac_f32_e32 v97, v47, v27
	v_add_f32_dpp v48, v48, v48 row_mirror row_mask:0xf bank_mask:0xf bound_ctrl:1
	v_fmac_f32_e32 v94, v32, v48
	v_fmac_f32_e32 v95, v33, v48
	v_fmac_f32_e32 v96, v34, v48
	v_fmac_f32_e32 v97, v35, v48
	v_mul_f32_e32 v48, v94, v0
	v_mul_f32_e32 v73, v94, v36
	v_fmac_f32_e32 v48, v95, v1
	v_fmac_f32_e32 v73, v95, v37
	v_fmac_f32_e32 v48, v96, v2
	v_fmac_f32_e32 v73, v96, v38
	v_fmac_f32_e32 v48, v97, v3
	v_fmac_f32_e32 v73, v97, v39
	ds_read_b128 v[0:3], v50 offset:25600
	ds_read_b128 v[28:31], v50 offset:23552
	ds_read_b128 v[24:27], v50 offset:23296
	ds_read_b128 v[32:35], v50 offset:24320
	ds_read_b128 v[36:39], v50 offset:23040
	s_waitcnt lgkmcnt(5)
; #define LAS __attribute__((address_space(3)))
; __device__ __forceinline__ float sum16(float x) { x += dpp_f<0xB1>(x); x += dpp_f<0x4E>(x); x += dpp_f<0x141>(x); x += dpp_f<0x140>(x); return x; }
; __device__ __forceinline__ void rwkv_scan_phase(LAS unsigned char* lds, const bf16_t* RKV, const float* DEC, const float* AF, const float* k_k, const float* k_a, const float* r_k, float* BON, float* Y, int bx, const int tid) {
;     ...
;             for (int t = 0; t < SC_T; ++t) {
;                 f32x4 r4n = r4, w4n = w4, k4n = k4, a4n = a4, b4n = b4; float vvn = vv;
;                 if (t + 1 < SC_T) { const LAS unsigned char* p = base + (t + 1) * SC_TOK;
;                     r4n = *(const LAS f32x4*)(p); w4n = *(const LAS f32x4*)(p + 256); k4n = *(const LAS f32x4*)(p + 512); a4n = *(const LAS f32x4*)(p + 1024); b4n = *(const LAS f32x4*)(p + 1280);
;                     vvn = *(const LAS float*)(vbase + (t + 1) * SC_TOK); }
;                 const f32x2 a01 = {a4[0], a4[1]}, a23 = {a4[2], a4[3]}, w01 = {w4[0], w4[1]}, w23 = {w4[2], w4[3]}, b01 = {b4[0], b4[1]}, b23 = {b4[2], b4[3]}, k01 = {k4[0], k4[1]}, k23 = {k4[2], k4[3]}, r01 = {r4[0], r4[1]}, r23 = {r4[2], r4[3]};
;                 const f32x2 tsa = S01 * a01 + S23 * a23; const float sa = sum16(tsa[0] + tsa[1]);
;                 S01 = S01 * w01 + (b01 * sa + k01 * vv); S23 = S23 * w23 + (b23 * sa + k23 * vv);
;                 const f32x2 ty = S01 * r01 + S23 * r23; const float y = sum16(ty[0] + ty[1]);
;                 ykeep = ((lane & 15) == (t & 15)) ? y : ykeep;
;                 if ((t & 15) == 15) yp[(size_t)(c * SC_T + (t - 15) + (lane & 15)) * 2048] = ykeep;
;                 r4 = r4n; w4 = w4n; k4 = k4n; a4 = a4n; b4 = b4n; vv = vvn;
;             }
	v_add_f32_dpp v48, v48, v48 quad_perm:[1,0,3,2] row_mask:0xf bank_mask:0xf bound_ctrl:1
	v_mul_f32_e32 v44, v8, v42
	v_mul_f32_e32 v45, v9, v42
	v_mul_f32_e32 v46, v10, v42
	v_add_f32_dpp v48, v48, v48 quad_perm:[2,3,0,1] row_mask:0xf bank_mask:0xf bound_ctrl:1
	v_mul_f32_e32 v47, v11, v42
	v_fmac_f32_e32 v44, v94, v4
	v_fmac_f32_e32 v45, v95, v5
	v_add_f32_dpp v48, v48, v48 row_half_mirror row_mask:0xf bank_mask:0xf bound_ctrl:1
	v_fmac_f32_e32 v46, v96, v6
	v_fmac_f32_e32 v47, v97, v7
	v_add_f32_dpp v48, v48, v48 row_mirror row_mask:0xf bank_mask:0xf bound_ctrl:1
	v_fmac_f32_e32 v44, v12, v48
	v_fmac_f32_e32 v45, v13, v48
	v_fmac_f32_e32 v46, v14, v48
	v_fmac_f32_e32 v47, v15, v48
	v_mul_f32_e32 v48, v44, v20
	v_mul_f32_e32 v74, v44, v16
	v_fmac_f32_e32 v48, v45, v21
	v_fmac_f32_e32 v74, v45, v17
	v_fmac_f32_e32 v48, v46, v22
	v_fmac_f32_e32 v74, v46, v18
	v_fmac_f32_e32 v48, v47, v23
	v_fmac_f32_e32 v74, v47, v19
	ds_read_b128 v[20:23], v50 offset:27136
	ds_read_b128 v[8:11], v50 offset:25088
	ds_read2st64_b32 v[40:41], v51 offset0:99 offset1:105
	ds_read_b128 v[4:7], v50 offset:24832
	ds_read_b128 v[12:15], v50 offset:25856
	ds_read_b128 v[16:19], v50 offset:24576
	s_waitcnt lgkmcnt(6)
	v_add_f32_dpp v48, v48, v48 quad_perm:[1,0,3,2] row_mask:0xf bank_mask:0xf bound_ctrl:1
	v_mul_f32_e32 v94, v28, v43
	v_mul_f32_e32 v95, v29, v43
	v_mul_f32_e32 v96, v30, v43
	v_add_f32_dpp v48, v48, v48 quad_perm:[2,3,0,1] row_mask:0xf bank_mask:0xf bound_ctrl:1
	v_mul_f32_e32 v97, v31, v43
	v_fmac_f32_e32 v94, v44, v24
	v_fmac_f32_e32 v95, v45, v25
	v_add_f32_dpp v48, v48, v48 row_half_mirror row_mask:0xf bank_mask:0xf bound_ctrl:1
	v_fmac_f32_e32 v96, v46, v26
	v_fmac_f32_e32 v97, v47, v27
	v_add_f32_dpp v48, v48, v48 row_mirror row_mask:0xf bank_mask:0xf bound_ctrl:1
	v_fmac_f32_e32 v94, v32, v48
	v_fmac_f32_e32 v95, v33, v48
	v_fmac_f32_e32 v96, v34, v48
	v_fmac_f32_e32 v97, v35, v48
	v_mul_f32_e32 v48, v94, v0
	v_mul_f32_e32 v75, v94, v36
	v_fmac_f32_e32 v48, v95, v1
	v_fmac_f32_e32 v75, v95, v37
	v_fmac_f32_e32 v48, v96, v2
	v_fmac_f32_e32 v75, v96, v38
	v_fmac_f32_e32 v48, v97, v3
	v_fmac_f32_e32 v75, v97, v39
	v_add_f32_dpp v60, v60, v60 row_mirror row_mask:0xf bank_mask:0x3 bound_ctrl:1
	v_add_f32_dpp v60, v68, v68 row_mirror row_mask:0xf bank_mask:0xc bound_ctrl:1
	v_add_f32_dpp v61, v61, v61 row_mirror row_mask:0xf bank_mask:0x3 bound_ctrl:1
	v_add_f32_dpp v61, v69, v69 row_mirror row_mask:0xf bank_mask:0xc bound_ctrl:1
	v_add_f32_dpp v62, v62, v62 row_mirror row_mask:0xf bank_mask:0x3 bound_ctrl:1
	v_add_f32_dpp v62, v70, v70 row_mirror row_mask:0xf bank_mask:0xc bound_ctrl:1
	v_add_f32_dpp v63, v63, v63 row_mirror row_mask:0xf bank_mask:0x3 bound_ctrl:1
	v_add_f32_dpp v63, v71, v71 row_mirror row_mask:0xf bank_mask:0xc bound_ctrl:1
	v_add_f32_dpp v64, v64, v64 row_mirror row_mask:0xf bank_mask:0x3 bound_ctrl:1
	v_add_f32_dpp v64, v72, v72 row_mirror row_mask:0xf bank_mask:0xc bound_ctrl:1
	v_add_f32_dpp v65, v65, v65 row_mirror row_mask:0xf bank_mask:0x3 bound_ctrl:1
	v_add_f32_dpp v65, v73, v73 row_mirror row_mask:0xf bank_mask:0xc bound_ctrl:1
	v_add_f32_dpp v66, v66, v66 row_mirror row_mask:0xf bank_mask:0x3 bound_ctrl:1
	v_add_f32_dpp v66, v74, v74 row_mirror row_mask:0xf bank_mask:0xc bound_ctrl:1
	v_add_f32_dpp v67, v67, v67 row_mirror row_mask:0xf bank_mask:0x3 bound_ctrl:1
	v_add_f32_dpp v67, v75, v75 row_mirror row_mask:0xf bank_mask:0xc bound_ctrl:1
	v_add_f32_dpp v60, v60, v60 row_half_mirror row_mask:0xf bank_mask:0x5 bound_ctrl:1
	v_add_f32_dpp v60, v64, v64 row_half_mirror row_mask:0xf bank_mask:0xa bound_ctrl:1
	v_add_f32_dpp v61, v61, v61 row_half_mirror row_mask:0xf bank_mask:0x5 bound_ctrl:1
	v_add_f32_dpp v61, v65, v65 row_half_mirror row_mask:0xf bank_mask:0xa bound_ctrl:1
	v_add_f32_dpp v62, v62, v62 row_half_mirror row_mask:0xf bank_mask:0x5 bound_ctrl:1
	v_add_f32_dpp v62, v66, v66 row_half_mirror row_mask:0xf bank_mask:0xa bound_ctrl:1
	v_add_f32_dpp v63, v63, v63 row_half_mirror row_mask:0xf bank_mask:0x5 bound_ctrl:1
	v_add_f32_dpp v63, v67, v67 row_half_mirror row_mask:0xf bank_mask:0xa bound_ctrl:1
	v_cndmask_b32_e64 v76, v62, v60, s[46:47]
	v_cndmask_b32_e64 v77, v63, v61, s[46:47]
	v_cndmask_b32_e64 v78, v60, v62, s[46:47]
	v_cndmask_b32_e64 v79, v61, v63, s[46:47]
	v_add_f32_dpp v60, v76, v78 quad_perm:[2,3,0,1] row_mask:0xf bank_mask:0xf bound_ctrl:1
	v_add_f32_dpp v61, v77, v79 quad_perm:[2,3,0,1] row_mask:0xf bank_mask:0xf bound_ctrl:1
	v_cndmask_b32_e64 v76, v61, v60, s[40:41]
	v_cndmask_b32_e64 v78, v60, v61, s[40:41]
	s_nop 1
	v_add_f32_dpp v60, v76, v78 quad_perm:[1,0,3,2] row_mask:0xf bank_mask:0xf bound_ctrl:1
	global_store_dword v[92:93], v60, off
	ds_read_b128 v[0:3], v50 offset:28672
	ds_read_b128 v[28:31], v50 offset:26624
	ds_read_b128 v[24:27], v50 offset:26368
	ds_read_b128 v[32:35], v50 offset:27392
	ds_read_b128 v[36:39], v50 offset:26112
	s_waitcnt lgkmcnt(5)
	v_add_f32_dpp v48, v48, v48 quad_perm:[1,0,3,2] row_mask:0xf bank_mask:0xf bound_ctrl:1
	v_mul_f32_e32 v44, v8, v40
	v_mul_f32_e32 v45, v9, v40
	v_mul_f32_e32 v46, v10, v40
	v_add_f32_dpp v48, v48, v48 quad_perm:[2,3,0,1] row_mask:0xf bank_mask:0xf bound_ctrl:1
	v_mul_f32_e32 v47, v11, v40
	v_fmac_f32_e32 v44, v94, v4
	v_fmac_f32_e32 v45, v95, v5
	v_add_f32_dpp v48, v48, v48 row_half_mirror row_mask:0xf bank_mask:0xf bound_ctrl:1
	v_fmac_f32_e32 v46, v96, v6
	v_fmac_f32_e32 v47, v97, v7
	v_add_f32_dpp v48, v48, v48 row_mirror row_mask:0xf bank_mask:0xf bound_ctrl:1
	v_fmac_f32_e32 v44, v12, v48
	v_fmac_f32_e32 v45, v13, v48
	v_fmac_f32_e32 v46, v14, v48
	v_fmac_f32_e32 v47, v15, v48
	v_mul_f32_e32 v48, v44, v20
	v_mul_f32_e32 v60, v44, v16
	v_fmac_f32_e32 v48, v45, v21
	v_fmac_f32_e32 v60, v45, v17
	v_fmac_f32_e32 v48, v46, v22
	v_fmac_f32_e32 v60, v46, v18
	v_fmac_f32_e32 v48, v47, v23
	v_fmac_f32_e32 v60, v47, v19
	ds_read_b128 v[20:23], v50 offset:30208
	ds_read_b128 v[8:11], v50 offset:28160
	ds_read2st64_b32 v[42:43], v51 offset0:111 offset1:117
	ds_read_b128 v[4:7], v50 offset:27904
	ds_read_b128 v[12:15], v50 offset:28928
	ds_read_b128 v[16:19], v50 offset:27648
	s_waitcnt lgkmcnt(6)
; #define LAS __attribute__((address_space(3)))
; __device__ __forceinline__ float sum16(float x) { x += dpp_f<0xB1>(x); x += dpp_f<0x4E>(x); x += dpp_f<0x141>(x); x += dpp_f<0x140>(x); return x; }
; __device__ __forceinline__ void rwkv_scan_phase(LAS unsigned char* lds, const bf16_t* RKV, const float* DEC, const float* AF, const float* k_k, const float* k_a, const float* r_k, float* BON, float* Y, int bx, const int tid) {
;     ...
;             for (int t = 0; t < SC_T; ++t) {
;                 f32x4 r4n = r4, w4n = w4, k4n = k4, a4n = a4, b4n = b4; float vvn = vv;
;                 if (t + 1 < SC_T) { const LAS unsigned char* p = base + (t + 1) * SC_TOK;
;                     r4n = *(const LAS f32x4*)(p); w4n = *(const LAS f32x4*)(p + 256); k4n = *(const LAS f32x4*)(p + 512); a4n = *(const LAS f32x4*)(p + 1024); b4n = *(const LAS f32x4*)(p + 1280);
;                     vvn = *(const LAS float*)(vbase + (t + 1) * SC_TOK); }
;                 const f32x2 a01 = {a4[0], a4[1]}, a23 = {a4[2], a4[3]}, w01 = {w4[0], w4[1]}, w23 = {w4[2], w4[3]}, b01 = {b4[0], b4[1]}, b23 = {b4[2], b4[3]}, k01 = {k4[0], k4[1]}, k23 = {k4[2], k4[3]}, r01 = {r4[0], r4[1]}, r23 = {r4[2], r4[3]};
;                 const f32x2 tsa = S01 * a01 + S23 * a23; const float sa = sum16(tsa[0] + tsa[1]);
;                 S01 = S01 * w01 + (b01 * sa + k01 * vv); S23 = S23 * w23 + (b23 * sa + k23 * vv);
;                 const f32x2 ty = S01 * r01 + S23 * r23; const float y = sum16(ty[0] + ty[1]);
;                 ykeep = ((lane & 15) == (t & 15)) ? y : ykeep;
;                 if ((t & 15) == 15) yp[(size_t)(c * SC_T + (t - 15) + (lane & 15)) * 2048] = ykeep;
;                 r4 = r4n; w4 = w4n; k4 = k4n; a4 = a4n; b4 = b4n; vv = vvn;
	v_add_f32_dpp v48, v48, v48 quad_perm:[1,0,3,2] row_mask:0xf bank_mask:0xf bound_ctrl:1
	v_mul_f32_e32 v94, v28, v41
	v_mul_f32_e32 v95, v29, v41
	v_mul_f32_e32 v96, v30, v41
	v_add_f32_dpp v48, v48, v48 quad_perm:[2,3,0,1] row_mask:0xf bank_mask:0xf bound_ctrl:1
	v_mul_f32_e32 v97, v31, v41
	v_fmac_f32_e32 v94, v44, v24
	v_fmac_f32_e32 v95, v45, v25
	v_add_f32_dpp v48, v48, v48 row_half_mirror row_mask:0xf bank_mask:0xf bound_ctrl:1
	v_fmac_f32_e32 v96, v46, v26
	v_fmac_f32_e32 v97, v47, v27
	v_add_f32_dpp v48, v48, v48 row_mirror row_mask:0xf bank_mask:0xf bound_ctrl:1
	v_fmac_f32_e32 v94, v32, v48
	v_fmac_f32_e32 v95, v33, v48
	v_fmac_f32_e32 v96, v34, v48
	v_fmac_f32_e32 v97, v35, v48
	v_mul_f32_e32 v48, v94, v0
	v_mul_f32_e32 v61, v94, v36
	v_fmac_f32_e32 v48, v95, v1
	v_fmac_f32_e32 v61, v95, v37
	v_fmac_f32_e32 v48, v96, v2
	v_fmac_f32_e32 v61, v96, v38
	v_fmac_f32_e32 v48, v97, v3
	v_fmac_f32_e32 v61, v97, v39
	ds_read_b128 v[0:3], v50 offset:31744
	ds_read_b128 v[28:31], v50 offset:29696
	ds_read_b128 v[24:27], v50 offset:29440
	ds_read_b128 v[32:35], v50 offset:30464
	ds_read_b128 v[36:39], v50 offset:29184
	s_waitcnt lgkmcnt(5)
	v_add_f32_dpp v48, v48, v48 quad_perm:[1,0,3,2] row_mask:0xf bank_mask:0xf bound_ctrl:1
	v_mul_f32_e32 v44, v8, v42
	v_mul_f32_e32 v45, v9, v42
	v_mul_f32_e32 v46, v10, v42
	v_add_f32_dpp v48, v48, v48 quad_perm:[2,3,0,1] row_mask:0xf bank_mask:0xf bound_ctrl:1
	v_mul_f32_e32 v47, v11, v42
	v_fmac_f32_e32 v44, v94, v4
	v_fmac_f32_e32 v45, v95, v5
	v_add_f32_dpp v48, v48, v48 row_half_mirror row_mask:0xf bank_mask:0xf bound_ctrl:1
	v_fmac_f32_e32 v46, v96, v6
	v_fmac_f32_e32 v47, v97, v7
	v_add_f32_dpp v48, v48, v48 row_mirror row_mask:0xf bank_mask:0xf bound_ctrl:1
	v_fmac_f32_e32 v44, v12, v48
	v_fmac_f32_e32 v45, v13, v48
	v_fmac_f32_e32 v46, v14, v48
	v_fmac_f32_e32 v47, v15, v48
	v_mul_f32_e32 v48, v44, v20
	v_mul_f32_e32 v62, v44, v16
	v_fmac_f32_e32 v48, v45, v21
	v_fmac_f32_e32 v62, v45, v17
	v_fmac_f32_e32 v48, v46, v22
	v_fmac_f32_e32 v62, v46, v18
	v_fmac_f32_e32 v48, v47, v23
	v_fmac_f32_e32 v62, v47, v19
	ds_read_b128 v[20:23], v50 offset:33280
	ds_read_b128 v[8:11], v50 offset:31232
	ds_read2st64_b32 v[40:41], v51 offset0:123 offset1:129
	ds_read_b128 v[4:7], v50 offset:30976
	ds_read_b128 v[12:15], v50 offset:32000
	ds_read_b128 v[16:19], v50 offset:30720
	s_waitcnt lgkmcnt(6)
	v_add_f32_dpp v48, v48, v48 quad_perm:[1,0,3,2] row_mask:0xf bank_mask:0xf bound_ctrl:1
	v_mul_f32_e32 v94, v28, v43
	v_mul_f32_e32 v95, v29, v43
	v_mul_f32_e32 v96, v30, v43
	v_add_f32_dpp v48, v48, v48 quad_perm:[2,3,0,1] row_mask:0xf bank_mask:0xf bound_ctrl:1
	v_mul_f32_e32 v97, v31, v43
	v_fmac_f32_e32 v94, v44, v24
	v_fmac_f32_e32 v95, v45, v25
	v_add_f32_dpp v48, v48, v48 row_half_mirror row_mask:0xf bank_mask:0xf bound_ctrl:1
	v_fmac_f32_e32 v96, v46, v26
	v_fmac_f32_e32 v97, v47, v27
	v_add_f32_dpp v48, v48, v48 row_mirror row_mask:0xf bank_mask:0xf bound_ctrl:1
	v_fmac_f32_e32 v94, v32, v48
	v_fmac_f32_e32 v95, v33, v48
	v_fmac_f32_e32 v96, v34, v48
	v_fmac_f32_e32 v97, v35, v48
	v_mul_f32_e32 v48, v94, v0
	v_mul_f32_e32 v63, v94, v36
	v_fmac_f32_e32 v48, v95, v1
	v_fmac_f32_e32 v63, v95, v37
	v_fmac_f32_e32 v48, v96, v2
	v_fmac_f32_e32 v63, v96, v38
	v_fmac_f32_e32 v48, v97, v3
	v_fmac_f32_e32 v63, v97, v39
	ds_read_b128 v[0:3], v50 offset:34816
	ds_read_b128 v[28:31], v50 offset:32768
	ds_read_b128 v[24:27], v50 offset:32512
	ds_read_b128 v[32:35], v50 offset:33536
	ds_read_b128 v[36:39], v50 offset:32256
	s_waitcnt lgkmcnt(5)
	v_add_f32_dpp v48, v48, v48 quad_perm:[1,0,3,2] row_mask:0xf bank_mask:0xf bound_ctrl:1
	v_mul_f32_e32 v44, v8, v40
	v_mul_f32_e32 v45, v9, v40
	v_mul_f32_e32 v46, v10, v40
	v_add_f32_dpp v48, v48, v48 quad_perm:[2,3,0,1] row_mask:0xf bank_mask:0xf bound_ctrl:1
	v_mul_f32_e32 v47, v11, v40
	v_fmac_f32_e32 v44, v94, v4
	v_fmac_f32_e32 v45, v95, v5
	v_add_f32_dpp v48, v48, v48 row_half_mirror row_mask:0xf bank_mask:0xf bound_ctrl:1
	v_fmac_f32_e32 v46, v96, v6
	v_fmac_f32_e32 v47, v97, v7
	v_add_f32_dpp v48, v48, v48 row_mirror row_mask:0xf bank_mask:0xf bound_ctrl:1
	v_fmac_f32_e32 v44, v12, v48
	v_fmac_f32_e32 v45, v13, v48
	v_fmac_f32_e32 v46, v14, v48
	v_fmac_f32_e32 v47, v15, v48
	v_mul_f32_e32 v48, v44, v20
	v_mul_f32_e32 v64, v44, v16
	v_fmac_f32_e32 v48, v45, v21
	v_fmac_f32_e32 v64, v45, v17
	v_fmac_f32_e32 v48, v46, v22
	v_fmac_f32_e32 v64, v46, v18
	v_fmac_f32_e32 v48, v47, v23
	v_fmac_f32_e32 v64, v47, v19
	ds_read_b128 v[20:23], v50 offset:36352
	ds_read_b128 v[8:11], v50 offset:34304
	ds_read2st64_b32 v[42:43], v51 offset0:135 offset1:141
	ds_read_b128 v[4:7], v50 offset:34048
	ds_read_b128 v[12:15], v50 offset:35072
	ds_read_b128 v[16:19], v50 offset:33792
	s_waitcnt lgkmcnt(6)
	v_add_f32_dpp v48, v48, v48 quad_perm:[1,0,3,2] row_mask:0xf bank_mask:0xf bound_ctrl:1
	v_mul_f32_e32 v94, v28, v41
	v_mul_f32_e32 v95, v29, v41
	v_mul_f32_e32 v96, v30, v41
	v_add_f32_dpp v48, v48, v48 quad_perm:[2,3,0,1] row_mask:0xf bank_mask:0xf bound_ctrl:1
	v_mul_f32_e32 v97, v31, v41
	v_fmac_f32_e32 v94, v44, v24
	v_fmac_f32_e32 v95, v45, v25
	v_add_f32_dpp v48, v48, v48 row_half_mirror row_mask:0xf bank_mask:0xf bound_ctrl:1
	v_fmac_f32_e32 v96, v46, v26
	v_fmac_f32_e32 v97, v47, v27
	v_add_f32_dpp v48, v48, v48 row_mirror row_mask:0xf bank_mask:0xf bound_ctrl:1
	v_fmac_f32_e32 v94, v32, v48
	v_fmac_f32_e32 v95, v33, v48
	v_fmac_f32_e32 v96, v34, v48
	v_fmac_f32_e32 v97, v35, v48
	v_mul_f32_e32 v48, v94, v0
	v_mul_f32_e32 v65, v94, v36
	v_fmac_f32_e32 v48, v95, v1
	v_fmac_f32_e32 v65, v95, v37
	v_fmac_f32_e32 v48, v96, v2
	v_fmac_f32_e32 v65, v96, v38
	v_fmac_f32_e32 v48, v97, v3
	v_fmac_f32_e32 v65, v97, v39
	ds_read_b128 v[0:3], v50 offset:37888
	ds_read_b128 v[28:31], v50 offset:35840
	ds_read_b128 v[24:27], v50 offset:35584
	ds_read_b128 v[32:35], v50 offset:36608
	ds_read_b128 v[36:39], v50 offset:35328
	s_waitcnt lgkmcnt(5)
; #define LAS __attribute__((address_space(3)))
; __device__ __forceinline__ float sum16(float x) { x += dpp_f<0xB1>(x); x += dpp_f<0x4E>(x); x += dpp_f<0x141>(x); x += dpp_f<0x140>(x); return x; }
; __device__ __forceinline__ void rwkv_scan_phase(LAS unsigned char* lds, const bf16_t* RKV, const float* DEC, const float* AF, const float* k_k, const float* k_a, const float* r_k, float* BON, float* Y, int bx, const int tid) {
;     ...
;             for (int t = 0; t < SC_T; ++t) {
;                 f32x4 r4n = r4, w4n = w4, k4n = k4, a4n = a4, b4n = b4; float vvn = vv;
;                 if (t + 1 < SC_T) { const LAS unsigned char* p = base + (t + 1) * SC_TOK;
;                     r4n = *(const LAS f32x4*)(p); w4n = *(const LAS f32x4*)(p + 256); k4n = *(const LAS f32x4*)(p + 512); a4n = *(const LAS f32x4*)(p + 1024); b4n = *(const LAS f32x4*)(p + 1280);
;                     vvn = *(const LAS float*)(vbase + (t + 1) * SC_TOK); }
;                 const f32x2 a01 = {a4[0], a4[1]}, a23 = {a4[2], a4[3]}, w01 = {w4[0], w4[1]}, w23 = {w4[2], w4[3]}, b01 = {b4[0], b4[1]}, b23 = {b4[2], b4[3]}, k01 = {k4[0], k4[1]}, k23 = {k4[2], k4[3]}, r01 = {r4[0], r4[1]}, r23 = {r4[2], r4[3]};
;                 const f32x2 tsa = S01 * a01 + S23 * a23; const float sa = sum16(tsa[0] + tsa[1]);
;                 S01 = S01 * w01 + (b01 * sa + k01 * vv); S23 = S23 * w23 + (b23 * sa + k23 * vv);
;                 const f32x2 ty = S01 * r01 + S23 * r23; const float y = sum16(ty[0] + ty[1]);
;                 ykeep = ((lane & 15) == (t & 15)) ? y : ykeep;
;                 if ((t & 15) == 15) yp[(size_t)(c * SC_T + (t - 15) + (lane & 15)) * 2048] = ykeep;
;                 r4 = r4n; w4 = w4n; k4 = k4n; a4 = a4n; b4 = b4n; vv = vvn;
	v_add_f32_dpp v48, v48, v48 quad_perm:[1,0,3,2] row_mask:0xf bank_mask:0xf bound_ctrl:1
	v_mul_f32_e32 v44, v8, v42
	v_mul_f32_e32 v45, v9, v42
	v_mul_f32_e32 v46, v10, v42
	v_add_f32_dpp v48, v48, v48 quad_perm:[2,3,0,1] row_mask:0xf bank_mask:0xf bound_ctrl:1
	v_mul_f32_e32 v47, v11, v42
	v_fmac_f32_e32 v44, v94, v4
	v_fmac_f32_e32 v45, v95, v5
	v_add_f32_dpp v48, v48, v48 row_half_mirror row_mask:0xf bank_mask:0xf bound_ctrl:1
	v_fmac_f32_e32 v46, v96, v6
	v_fmac_f32_e32 v47, v97, v7
	v_add_f32_dpp v48, v48, v48 row_mirror row_mask:0xf bank_mask:0xf bound_ctrl:1
	v_fmac_f32_e32 v44, v12, v48
	v_fmac_f32_e32 v45, v13, v48
	v_fmac_f32_e32 v46, v14, v48
	v_fmac_f32_e32 v47, v15, v48
	v_mul_f32_e32 v48, v44, v20
	v_mul_f32_e32 v66, v44, v16
	v_fmac_f32_e32 v48, v45, v21
	v_fmac_f32_e32 v66, v45, v17
	v_fmac_f32_e32 v48, v46, v22
	v_fmac_f32_e32 v66, v46, v18
	v_fmac_f32_e32 v48, v47, v23
	v_fmac_f32_e32 v66, v47, v19
	ds_read_b128 v[20:23], v50 offset:39424
	ds_read_b128 v[8:11], v50 offset:37376
	ds_read2st64_b32 v[40:41], v51 offset0:147 offset1:153
	ds_read_b128 v[4:7], v50 offset:37120
	ds_read_b128 v[12:15], v50 offset:38144
	ds_read_b128 v[16:19], v50 offset:36864
	s_waitcnt lgkmcnt(6)
	v_add_f32_dpp v48, v48, v48 quad_perm:[1,0,3,2] row_mask:0xf bank_mask:0xf bound_ctrl:1
	v_mul_f32_e32 v94, v28, v43
	v_mul_f32_e32 v95, v29, v43
	v_mul_f32_e32 v96, v30, v43
	v_add_f32_dpp v48, v48, v48 quad_perm:[2,3,0,1] row_mask:0xf bank_mask:0xf bound_ctrl:1
	v_mul_f32_e32 v97, v31, v43
	v_fmac_f32_e32 v94, v44, v24
	v_fmac_f32_e32 v95, v45, v25
	v_add_f32_dpp v48, v48, v48 row_half_mirror row_mask:0xf bank_mask:0xf bound_ctrl:1
	v_fmac_f32_e32 v96, v46, v26
	v_fmac_f32_e32 v97, v47, v27
	v_add_f32_dpp v48, v48, v48 row_mirror row_mask:0xf bank_mask:0xf bound_ctrl:1
	v_fmac_f32_e32 v94, v32, v48
	v_fmac_f32_e32 v95, v33, v48
	v_fmac_f32_e32 v96, v34, v48
	v_fmac_f32_e32 v97, v35, v48
	v_mul_f32_e32 v48, v94, v0
	v_mul_f32_e32 v67, v94, v36
	v_fmac_f32_e32 v48, v95, v1
	v_fmac_f32_e32 v67, v95, v37
	v_fmac_f32_e32 v48, v96, v2
	v_fmac_f32_e32 v67, v96, v38
	v_fmac_f32_e32 v48, v97, v3
	v_fmac_f32_e32 v67, v97, v39
	ds_read_b128 v[0:3], v50 offset:40960
	ds_read_b128 v[28:31], v50 offset:38912
	ds_read_b128 v[24:27], v50 offset:38656
	ds_read_b128 v[32:35], v50 offset:39680
	ds_read_b128 v[36:39], v50 offset:38400
	s_waitcnt lgkmcnt(5)
	v_add_f32_dpp v48, v48, v48 quad_perm:[1,0,3,2] row_mask:0xf bank_mask:0xf bound_ctrl:1
	v_mul_f32_e32 v44, v8, v40
	v_mul_f32_e32 v45, v9, v40
	v_mul_f32_e32 v46, v10, v40
	v_add_f32_dpp v48, v48, v48 quad_perm:[2,3,0,1] row_mask:0xf bank_mask:0xf bound_ctrl:1
	v_mul_f32_e32 v47, v11, v40
	v_fmac_f32_e32 v44, v94, v4
	v_fmac_f32_e32 v45, v95, v5
	v_add_f32_dpp v48, v48, v48 row_half_mirror row_mask:0xf bank_mask:0xf bound_ctrl:1
	v_fmac_f32_e32 v46, v96, v6
	v_fmac_f32_e32 v47, v97, v7
	v_add_f32_dpp v48, v48, v48 row_mirror row_mask:0xf bank_mask:0xf bound_ctrl:1
	v_fmac_f32_e32 v44, v12, v48
	v_fmac_f32_e32 v45, v13, v48
	v_fmac_f32_e32 v46, v14, v48
	v_fmac_f32_e32 v47, v15, v48
	v_mul_f32_e32 v48, v44, v20
	v_mul_f32_e32 v68, v44, v16
	v_fmac_f32_e32 v48, v45, v21
	v_fmac_f32_e32 v68, v45, v17
	v_fmac_f32_e32 v48, v46, v22
	v_fmac_f32_e32 v68, v46, v18
	v_fmac_f32_e32 v48, v47, v23
	v_fmac_f32_e32 v68, v47, v19
	ds_read_b128 v[20:23], v50 offset:42496
	ds_read_b128 v[8:11], v50 offset:40448
	ds_read2st64_b32 v[42:43], v51 offset0:159 offset1:165
	ds_read_b128 v[4:7], v50 offset:40192
	ds_read_b128 v[12:15], v50 offset:41216
	ds_read_b128 v[16:19], v50 offset:39936
	s_waitcnt lgkmcnt(6)
	v_add_f32_dpp v48, v48, v48 quad_perm:[1,0,3,2] row_mask:0xf bank_mask:0xf bound_ctrl:1
	v_mul_f32_e32 v94, v28, v41
	v_mul_f32_e32 v95, v29, v41
	v_mul_f32_e32 v96, v30, v41
	v_add_f32_dpp v48, v48, v48 quad_perm:[2,3,0,1] row_mask:0xf bank_mask:0xf bound_ctrl:1
	v_mul_f32_e32 v97, v31, v41
	v_fmac_f32_e32 v94, v44, v24
	v_fmac_f32_e32 v95, v45, v25
	v_add_f32_dpp v48, v48, v48 row_half_mirror row_mask:0xf bank_mask:0xf bound_ctrl:1
	v_fmac_f32_e32 v96, v46, v26
	v_fmac_f32_e32 v97, v47, v27
	v_add_f32_dpp v48, v48, v48 row_mirror row_mask:0xf bank_mask:0xf bound_ctrl:1
	v_fmac_f32_e32 v94, v32, v48
	v_fmac_f32_e32 v95, v33, v48
	v_fmac_f32_e32 v96, v34, v48
	v_fmac_f32_e32 v97, v35, v48
	v_mul_f32_e32 v48, v94, v0
	v_mul_f32_e32 v69, v94, v36
	v_fmac_f32_e32 v48, v95, v1
	v_fmac_f32_e32 v69, v95, v37
	v_fmac_f32_e32 v48, v96, v2
	v_fmac_f32_e32 v69, v96, v38
	v_fmac_f32_e32 v48, v97, v3
	v_fmac_f32_e32 v69, v97, v39
	ds_read_b128 v[0:3], v50 offset:44032
	ds_read_b128 v[28:31], v50 offset:41984
	ds_read_b128 v[24:27], v50 offset:41728
	ds_read_b128 v[32:35], v50 offset:42752
	ds_read_b128 v[36:39], v50 offset:41472
	s_waitcnt lgkmcnt(5)
	v_add_f32_dpp v48, v48, v48 quad_perm:[1,0,3,2] row_mask:0xf bank_mask:0xf bound_ctrl:1
	v_mul_f32_e32 v44, v8, v42
	v_mul_f32_e32 v45, v9, v42
	v_mul_f32_e32 v46, v10, v42
	v_add_f32_dpp v48, v48, v48 quad_perm:[2,3,0,1] row_mask:0xf bank_mask:0xf bound_ctrl:1
	v_mul_f32_e32 v47, v11, v42
	v_fmac_f32_e32 v44, v94, v4
	v_fmac_f32_e32 v45, v95, v5
	v_add_f32_dpp v48, v48, v48 row_half_mirror row_mask:0xf bank_mask:0xf bound_ctrl:1
	v_fmac_f32_e32 v46, v96, v6
	v_fmac_f32_e32 v47, v97, v7
	v_add_f32_dpp v48, v48, v48 row_mirror row_mask:0xf bank_mask:0xf bound_ctrl:1
	v_fmac_f32_e32 v44, v12, v48
	v_fmac_f32_e32 v45, v13, v48
	v_fmac_f32_e32 v46, v14, v48
	v_fmac_f32_e32 v47, v15, v48
	v_mul_f32_e32 v48, v44, v20
	v_mul_f32_e32 v70, v44, v16
	v_fmac_f32_e32 v48, v45, v21
	v_fmac_f32_e32 v70, v45, v17
	v_fmac_f32_e32 v48, v46, v22
	v_fmac_f32_e32 v70, v46, v18
	v_fmac_f32_e32 v48, v47, v23
	v_fmac_f32_e32 v70, v47, v19
	ds_read_b128 v[20:23], v50 offset:45568
	ds_read_b128 v[8:11], v50 offset:43520
	ds_read2st64_b32 v[40:41], v51 offset0:171 offset1:177
	ds_read_b128 v[4:7], v50 offset:43264
	ds_read_b128 v[12:15], v50 offset:44288
	ds_read_b128 v[16:19], v50 offset:43008
	s_waitcnt lgkmcnt(6)
; #define LAS __attribute__((address_space(3)))
; __device__ __forceinline__ float sum16(float x) { x += dpp_f<0xB1>(x); x += dpp_f<0x4E>(x); x += dpp_f<0x141>(x); x += dpp_f<0x140>(x); return x; }
; __device__ __forceinline__ void rwkv_scan_phase(LAS unsigned char* lds, const bf16_t* RKV, const float* DEC, const float* AF, const float* k_k, const float* k_a, const float* r_k, float* BON, float* Y, int bx, const int tid) {
;     ...
;             for (int t = 0; t < SC_T; ++t) {
;                 f32x4 r4n = r4, w4n = w4, k4n = k4, a4n = a4, b4n = b4; float vvn = vv;
;                 if (t + 1 < SC_T) { const LAS unsigned char* p = base + (t + 1) * SC_TOK;
;                     r4n = *(const LAS f32x4*)(p); w4n = *(const LAS f32x4*)(p + 256); k4n = *(const LAS f32x4*)(p + 512); a4n = *(const LAS f32x4*)(p + 1024); b4n = *(const LAS f32x4*)(p + 1280);
;                     vvn = *(const LAS float*)(vbase + (t + 1) * SC_TOK); }
;                 const f32x2 a01 = {a4[0], a4[1]}, a23 = {a4[2], a4[3]}, w01 = {w4[0], w4[1]}, w23 = {w4[2], w4[3]}, b01 = {b4[0], b4[1]}, b23 = {b4[2], b4[3]}, k01 = {k4[0], k4[1]}, k23 = {k4[2], k4[3]}, r01 = {r4[0], r4[1]}, r23 = {r4[2], r4[3]};
;                 const f32x2 tsa = S01 * a01 + S23 * a23; const float sa = sum16(tsa[0] + tsa[1]);
;                 S01 = S01 * w01 + (b01 * sa + k01 * vv); S23 = S23 * w23 + (b23 * sa + k23 * vv);
;                 const f32x2 ty = S01 * r01 + S23 * r23; const float y = sum16(ty[0] + ty[1]);
;                 ykeep = ((lane & 15) == (t & 15)) ? y : ykeep;
;                 if ((t & 15) == 15) yp[(size_t)(c * SC_T + (t - 15) + (lane & 15)) * 2048] = ykeep;
;                 r4 = r4n; w4 = w4n; k4 = k4n; a4 = a4n; b4 = b4n; vv = vvn;
	v_add_f32_dpp v48, v48, v48 quad_perm:[1,0,3,2] row_mask:0xf bank_mask:0xf bound_ctrl:1
	v_mul_f32_e32 v94, v28, v43
	v_mul_f32_e32 v95, v29, v43
	v_mul_f32_e32 v96, v30, v43
	v_add_f32_dpp v48, v48, v48 quad_perm:[2,3,0,1] row_mask:0xf bank_mask:0xf bound_ctrl:1
	v_mul_f32_e32 v97, v31, v43
	v_fmac_f32_e32 v94, v44, v24
	v_fmac_f32_e32 v95, v45, v25
	v_add_f32_dpp v48, v48, v48 row_half_mirror row_mask:0xf bank_mask:0xf bound_ctrl:1
	v_fmac_f32_e32 v96, v46, v26
	v_fmac_f32_e32 v97, v47, v27
	v_add_f32_dpp v48, v48, v48 row_mirror row_mask:0xf bank_mask:0xf bound_ctrl:1
	v_fmac_f32_e32 v94, v32, v48
	v_fmac_f32_e32 v95, v33, v48
	v_fmac_f32_e32 v96, v34, v48
	v_fmac_f32_e32 v97, v35, v48
	v_mul_f32_e32 v48, v94, v0
	v_mul_f32_e32 v71, v94, v36
	v_fmac_f32_e32 v48, v95, v1
	v_fmac_f32_e32 v71, v95, v37
	v_fmac_f32_e32 v48, v96, v2
	v_fmac_f32_e32 v71, v96, v38
	v_fmac_f32_e32 v48, v97, v3
	v_fmac_f32_e32 v71, v97, v39
	ds_read_b128 v[0:3], v50 offset:47104
	ds_read_b128 v[28:31], v50 offset:45056
	ds_read_b128 v[24:27], v50 offset:44800
	ds_read_b128 v[32:35], v50 offset:45824
	ds_read_b128 v[36:39], v50 offset:44544
	s_waitcnt lgkmcnt(5)
	v_add_f32_dpp v48, v48, v48 quad_perm:[1,0,3,2] row_mask:0xf bank_mask:0xf bound_ctrl:1
	v_mul_f32_e32 v44, v8, v40
	v_mul_f32_e32 v45, v9, v40
	v_mul_f32_e32 v46, v10, v40
	v_add_f32_dpp v48, v48, v48 quad_perm:[2,3,0,1] row_mask:0xf bank_mask:0xf bound_ctrl:1
	v_mul_f32_e32 v47, v11, v40
	v_fmac_f32_e32 v44, v94, v4
	v_fmac_f32_e32 v45, v95, v5
	v_add_f32_dpp v48, v48, v48 row_half_mirror row_mask:0xf bank_mask:0xf bound_ctrl:1
	v_fmac_f32_e32 v46, v96, v6
	v_fmac_f32_e32 v47, v97, v7
	v_add_f32_dpp v48, v48, v48 row_mirror row_mask:0xf bank_mask:0xf bound_ctrl:1
	v_fmac_f32_e32 v44, v12, v48
	v_fmac_f32_e32 v45, v13, v48
	v_fmac_f32_e32 v46, v14, v48
	v_fmac_f32_e32 v47, v15, v48
	v_mul_f32_e32 v48, v44, v20
	v_mul_f32_e32 v72, v44, v16
	v_fmac_f32_e32 v48, v45, v21
	v_fmac_f32_e32 v72, v45, v17
	v_fmac_f32_e32 v48, v46, v22
	v_fmac_f32_e32 v72, v46, v18
	v_fmac_f32_e32 v48, v47, v23
	v_fmac_f32_e32 v72, v47, v19
	ds_read_b128 v[20:23], v50 offset:48640
	ds_read_b128 v[8:11], v50 offset:46592
	ds_read2st64_b32 v[42:43], v51 offset0:183 offset1:189
	ds_read_b128 v[4:7], v50 offset:46336
	ds_read_b128 v[12:15], v50 offset:47360
	ds_read_b128 v[16:19], v50 offset:46080
	s_waitcnt lgkmcnt(6)
	v_add_f32_dpp v48, v48, v48 quad_perm:[1,0,3,2] row_mask:0xf bank_mask:0xf bound_ctrl:1
	v_mul_f32_e32 v94, v28, v41
	v_mul_f32_e32 v95, v29, v41
	v_mul_f32_e32 v96, v30, v41
	v_add_f32_dpp v48, v48, v48 quad_perm:[2,3,0,1] row_mask:0xf bank_mask:0xf bound_ctrl:1
	v_mul_f32_e32 v97, v31, v41
	v_fmac_f32_e32 v94, v44, v24
	v_fmac_f32_e32 v95, v45, v25
	v_add_f32_dpp v48, v48, v48 row_half_mirror row_mask:0xf bank_mask:0xf bound_ctrl:1
	v_fmac_f32_e32 v96, v46, v26
	v_fmac_f32_e32 v97, v47, v27
	v_add_f32_dpp v48, v48, v48 row_mirror row_mask:0xf bank_mask:0xf bound_ctrl:1
	v_fmac_f32_e32 v94, v32, v48
	v_fmac_f32_e32 v95, v33, v48
	v_fmac_f32_e32 v96, v34, v48
	v_fmac_f32_e32 v97, v35, v48
	v_mul_f32_e32 v48, v94, v0
	v_mul_f32_e32 v73, v94, v36
	v_fmac_f32_e32 v48, v95, v1
	v_fmac_f32_e32 v73, v95, v37
	v_fmac_f32_e32 v48, v96, v2
	v_fmac_f32_e32 v73, v96, v38
	v_fmac_f32_e32 v48, v97, v3
	v_fmac_f32_e32 v73, v97, v39
	ds_read_b128 v[28:31], v50 offset:48128
	ds_read_b128 v[24:27], v50 offset:47872
	ds_read_b128 v[32:35], v50 offset:48896
	ds_read_b128 v[36:39], v50 offset:47616
	s_waitcnt lgkmcnt(4)
; #define LAS __attribute__((address_space(3)))
; __device__ __forceinline__ float sum16(float x) { x += dpp_f<0xB1>(x); x += dpp_f<0x4E>(x); x += dpp_f<0x141>(x); x += dpp_f<0x140>(x); return x; }
; __device__ __forceinline__ void rwkv_scan_phase(LAS unsigned char* lds, const bf16_t* RKV, const float* DEC, const float* AF, const float* k_k, const float* k_a, const float* r_k, float* BON, float* Y, int bx, const int tid) {
;     ...
;             for (int t = 0; t < SC_T; ++t) {
;                 f32x4 r4n = r4, w4n = w4, k4n = k4, a4n = a4, b4n = b4; float vvn = vv;
;                 if (t + 1 < SC_T) { const LAS unsigned char* p = base + (t + 1) * SC_TOK;
;                     r4n = *(const LAS f32x4*)(p); w4n = *(const LAS f32x4*)(p + 256); k4n = *(const LAS f32x4*)(p + 512); a4n = *(const LAS f32x4*)(p + 1024); b4n = *(const LAS f32x4*)(p + 1280);
;                     vvn = *(const LAS float*)(vbase + (t + 1) * SC_TOK); }
;                 const f32x2 a01 = {a4[0], a4[1]}, a23 = {a4[2], a4[3]}, w01 = {w4[0], w4[1]}, w23 = {w4[2], w4[3]}, b01 = {b4[0], b4[1]}, b23 = {b4[2], b4[3]}, k01 = {k4[0], k4[1]}, k23 = {k4[2], k4[3]}, r01 = {r4[0], r4[1]}, r23 = {r4[2], r4[3]};
;                 const f32x2 tsa = S01 * a01 + S23 * a23; const float sa = sum16(tsa[0] + tsa[1]);
;                 S01 = S01 * w01 + (b01 * sa + k01 * vv); S23 = S23 * w23 + (b23 * sa + k23 * vv);
;                 const f32x2 ty = S01 * r01 + S23 * r23; const float y = sum16(ty[0] + ty[1]);
;                 ykeep = ((lane & 15) == (t & 15)) ? y : ykeep;
;                 if ((t & 15) == 15) yp[(size_t)(c * SC_T + (t - 15) + (lane & 15)) * 2048] = ykeep;
;                 r4 = r4n; w4 = w4n; k4 = k4n; a4 = a4n; b4 = b4n; vv = vvn;
;             }
	v_add_f32_dpp v48, v48, v48 quad_perm:[1,0,3,2] row_mask:0xf bank_mask:0xf bound_ctrl:1
	v_mul_f32_e32 v44, v8, v42
	v_mul_f32_e32 v45, v9, v42
	v_mul_f32_e32 v46, v10, v42
	v_add_f32_dpp v48, v48, v48 quad_perm:[2,3,0,1] row_mask:0xf bank_mask:0xf bound_ctrl:1
	v_mul_f32_e32 v47, v11, v42
	v_fmac_f32_e32 v44, v94, v4
	v_fmac_f32_e32 v45, v95, v5
	v_add_f32_dpp v48, v48, v48 row_half_mirror row_mask:0xf bank_mask:0xf bound_ctrl:1
	v_fmac_f32_e32 v46, v96, v6
	v_fmac_f32_e32 v47, v97, v7
	v_add_f32_dpp v48, v48, v48 row_mirror row_mask:0xf bank_mask:0xf bound_ctrl:1
	v_fmac_f32_e32 v44, v12, v48
	v_fmac_f32_e32 v45, v13, v48
	v_fmac_f32_e32 v46, v14, v48
	v_fmac_f32_e32 v47, v15, v48
	v_mul_f32_e32 v48, v44, v20
	v_mul_f32_e32 v74, v44, v16
	v_fmac_f32_e32 v48, v45, v21
	v_fmac_f32_e32 v74, v45, v17
	v_fmac_f32_e32 v48, v46, v22
	v_fmac_f32_e32 v74, v46, v18
	v_fmac_f32_e32 v48, v47, v23
	v_fmac_f32_e32 v74, v47, v19
	s_waitcnt lgkmcnt(0)
	s_nop 0
	v_add_f32_dpp v48, v48, v48 quad_perm:[1,0,3,2] row_mask:0xf bank_mask:0xf bound_ctrl:1
	v_mul_f32_e32 v94, v28, v43
	v_mul_f32_e32 v95, v29, v43
	v_mul_f32_e32 v96, v30, v43
	v_add_f32_dpp v48, v48, v48 quad_perm:[2,3,0,1] row_mask:0xf bank_mask:0xf bound_ctrl:1
	v_mul_f32_e32 v97, v31, v43
	v_fmac_f32_e32 v94, v44, v24
	v_fmac_f32_e32 v95, v45, v25
	v_add_f32_dpp v48, v48, v48 row_half_mirror row_mask:0xf bank_mask:0xf bound_ctrl:1
	v_fmac_f32_e32 v96, v46, v26
	v_fmac_f32_e32 v97, v47, v27
	v_add_f32_dpp v48, v48, v48 row_mirror row_mask:0xf bank_mask:0xf bound_ctrl:1
	v_fmac_f32_e32 v94, v32, v48
	v_fmac_f32_e32 v95, v33, v48
	v_fmac_f32_e32 v96, v34, v48
	v_fmac_f32_e32 v97, v35, v48
	v_mul_f32_e32 v75, v94, v36
	v_fmac_f32_e32 v75, v95, v37
	v_fmac_f32_e32 v75, v96, v38
	v_fmac_f32_e32 v75, v97, v39
	v_add_f32_dpp v60, v60, v60 row_mirror row_mask:0xf bank_mask:0x3 bound_ctrl:1
	v_add_f32_dpp v60, v68, v68 row_mirror row_mask:0xf bank_mask:0xc bound_ctrl:1
	v_add_f32_dpp v61, v61, v61 row_mirror row_mask:0xf bank_mask:0x3 bound_ctrl:1
	v_add_f32_dpp v61, v69, v69 row_mirror row_mask:0xf bank_mask:0xc bound_ctrl:1
	v_add_f32_dpp v62, v62, v62 row_mirror row_mask:0xf bank_mask:0x3 bound_ctrl:1
	v_add_f32_dpp v62, v70, v70 row_mirror row_mask:0xf bank_mask:0xc bound_ctrl:1
	v_add_f32_dpp v63, v63, v63 row_mirror row_mask:0xf bank_mask:0x3 bound_ctrl:1
	v_add_f32_dpp v63, v71, v71 row_mirror row_mask:0xf bank_mask:0xc bound_ctrl:1
	v_add_f32_dpp v64, v64, v64 row_mirror row_mask:0xf bank_mask:0x3 bound_ctrl:1
	v_add_f32_dpp v64, v72, v72 row_mirror row_mask:0xf bank_mask:0xc bound_ctrl:1
	v_add_f32_dpp v65, v65, v65 row_mirror row_mask:0xf bank_mask:0x3 bound_ctrl:1
	v_add_f32_dpp v65, v73, v73 row_mirror row_mask:0xf bank_mask:0xc bound_ctrl:1
	v_add_f32_dpp v66, v66, v66 row_mirror row_mask:0xf bank_mask:0x3 bound_ctrl:1
	v_add_f32_dpp v66, v74, v74 row_mirror row_mask:0xf bank_mask:0xc bound_ctrl:1
	v_add_f32_dpp v67, v67, v67 row_mirror row_mask:0xf bank_mask:0x3 bound_ctrl:1
	v_add_f32_dpp v67, v75, v75 row_mirror row_mask:0xf bank_mask:0xc bound_ctrl:1
	v_add_f32_dpp v60, v60, v60 row_half_mirror row_mask:0xf bank_mask:0x5 bound_ctrl:1
	v_add_f32_dpp v60, v64, v64 row_half_mirror row_mask:0xf bank_mask:0xa bound_ctrl:1
	v_add_f32_dpp v61, v61, v61 row_half_mirror row_mask:0xf bank_mask:0x5 bound_ctrl:1
	v_add_f32_dpp v61, v65, v65 row_half_mirror row_mask:0xf bank_mask:0xa bound_ctrl:1
	v_add_f32_dpp v62, v62, v62 row_half_mirror row_mask:0xf bank_mask:0x5 bound_ctrl:1
	v_add_f32_dpp v62, v66, v66 row_half_mirror row_mask:0xf bank_mask:0xa bound_ctrl:1
	v_add_f32_dpp v63, v63, v63 row_half_mirror row_mask:0xf bank_mask:0x5 bound_ctrl:1
	v_add_f32_dpp v63, v67, v67 row_half_mirror row_mask:0xf bank_mask:0xa bound_ctrl:1
	v_cndmask_b32_e64 v76, v62, v60, s[46:47]
	v_cndmask_b32_e64 v77, v63, v61, s[46:47]
	v_cndmask_b32_e64 v78, v60, v62, s[46:47]
	v_cndmask_b32_e64 v79, v61, v63, s[46:47]
	v_add_f32_dpp v60, v76, v78 quad_perm:[2,3,0,1] row_mask:0xf bank_mask:0xf bound_ctrl:1
	v_add_f32_dpp v61, v77, v79 quad_perm:[2,3,0,1] row_mask:0xf bank_mask:0xf bound_ctrl:1
	v_cndmask_b32_e64 v76, v61, v60, s[40:41]
	v_cndmask_b32_e64 v78, v60, v61, s[40:41]
	v_lshl_add_u64 v[52:53], v[92:93], 0, s[76:77]
	s_nop 0
	v_add_f32_dpp v60, v76, v78 quad_perm:[1,0,3,2] row_mask:0xf bank_mask:0xf bound_ctrl:1
	global_store_dword v[52:53], v60, off
	s_branch .LBB0_223

; __device__ __forceinline__ void mla_attn_phase(LAS unsigned char* lds, const bf16_t* Q, const bf16_t* KN, const bf16_t* KR, const bf16_t* VT, bf16_t* O, int G, int bx, const int tid) {
;     ...
;                 float mx = st[0][0];
; #pragma unroll
;                 for (int r = 1; r < 16; ++r) mx = fmaxf(mx, st[0][r]);
; #pragma unroll
;                 for (int r = 0; r < 16; ++r) mx = fmaxf(mx, st[1][r]);
;                 mx = fmaxf(mx, __shfl_xor(mx, 32));
;                 const float mnew = (mx > mrun + 8.0f) ? mx : mrun;
;                 if (__any(mnew != mrun)) { const float alpha = __builtin_amdgcn_exp2f(mrun - mnew); lrun *= alpha;
; #pragma unroll
;                     for (int i = 0; i < 4; ++i)
; #pragma unroll
;                         for (int r = 0; r < 16; ++r) o[i][r] *= alpha;
;                     mrun = mnew; }
.LBB0_284:
	v_add_u32_e32 v164, s60, v231
	v_add_u32_e32 v236, v164, v230
	s_nop 4
	v_max_f32_e32 v164, v81, v81
	v_max_f32_e32 v165, v80, v80
	v_max_f32_e32 v164, v165, v164
	v_max3_f32 v164, v164, v82, v83
	v_max3_f32 v164, v164, v84, v85
	v_max3_f32 v164, v164, v86, v87
	v_max3_f32 v164, v164, v88, v89
	v_max3_f32 v164, v164, v90, v91
	v_max3_f32 v164, v164, v92, v93
	v_max3_f32 v164, v164, v94, v95
	v_max3_f32 v164, v164, v64, v65
	v_max3_f32 v164, v164, v66, v67
	v_max3_f32 v164, v164, v68, v69
	v_max3_f32 v164, v164, v70, v71
	v_max3_f32 v164, v164, v72, v73
	v_max3_f32 v164, v164, v74, v75
	v_max3_f32 v164, v164, v76, v77
	v_max3_f32 v237, v164, v78, v79
	ds_read_b128 v[176:179], v236 offset:25600
	ds_read_b128 v[172:175], v236 offset:30208
	v_mov_b32_e32 v238, v237
	ds_read_b128 v[168:171], v236 offset:34816
	ds_read_b128 v[164:167], v236 offset:39424
	v_permlane32_swap_b32_e32 v237, v238
	v_max_f32_e32 v237, v237, v238
	v_add_f32_e32 v238, 0x41000000, v235
	v_cmp_gt_f32_e32 vcc, v237, v238
	s_nop 1
	v_cndmask_b32_e32 v237, v235, v237, vcc
	v_cmp_neq_f32_e32 vcc, v237, v235
	s_cbranch_vccz .LBB0_286
	v_sub_f32_e32 v235, v235, v237
	v_exp_f32_e32 v238, v235
	v_mov_b32_e32 v235, v237
	v_pk_mul_f32 v[62:63], v[62:63], v[238:239] op_sel_hi:[1,0]
	v_pk_mul_f32 v[60:61], v[60:61], v[238:239] op_sel_hi:[1,0]
	v_pk_mul_f32 v[58:59], v[58:59], v[238:239] op_sel_hi:[1,0]
	v_pk_mul_f32 v[56:57], v[56:57], v[238:239] op_sel_hi:[1,0]
	v_pk_mul_f32 v[54:55], v[54:55], v[238:239] op_sel_hi:[1,0]
	v_pk_mul_f32 v[52:53], v[52:53], v[238:239] op_sel_hi:[1,0]
	v_pk_mul_f32 v[50:51], v[50:51], v[238:239] op_sel_hi:[1,0]
	v_pk_mul_f32 v[48:49], v[48:49], v[238:239] op_sel_hi:[1,0]
	v_pk_mul_f32 v[46:47], v[46:47], v[238:239] op_sel_hi:[1,0]
	v_pk_mul_f32 v[44:45], v[44:45], v[238:239] op_sel_hi:[1,0]
	v_pk_mul_f32 v[42:43], v[42:43], v[238:239] op_sel_hi:[1,0]
	v_pk_mul_f32 v[40:41], v[40:41], v[238:239] op_sel_hi:[1,0]
	v_pk_mul_f32 v[38:39], v[38:39], v[238:239] op_sel_hi:[1,0]
	v_pk_mul_f32 v[36:37], v[36:37], v[238:239] op_sel_hi:[1,0]
	v_pk_mul_f32 v[34:35], v[34:35], v[238:239] op_sel_hi:[1,0]
	v_pk_mul_f32 v[32:33], v[32:33], v[238:239] op_sel_hi:[1,0]
	v_pk_mul_f32 v[30:31], v[30:31], v[238:239] op_sel_hi:[1,0]
	v_pk_mul_f32 v[28:29], v[28:29], v[238:239] op_sel_hi:[1,0]
	v_pk_mul_f32 v[26:27], v[26:27], v[238:239] op_sel_hi:[1,0]
	v_pk_mul_f32 v[24:25], v[24:25], v[238:239] op_sel_hi:[1,0]
	v_pk_mul_f32 v[22:23], v[22:23], v[238:239] op_sel_hi:[1,0]
	v_pk_mul_f32 v[20:21], v[20:21], v[238:239] op_sel_hi:[1,0]
	v_pk_mul_f32 v[18:19], v[18:19], v[238:239] op_sel_hi:[1,0]
	v_pk_mul_f32 v[16:17], v[16:17], v[238:239] op_sel_hi:[1,0]
	v_pk_mul_f32 v[14:15], v[14:15], v[238:239] op_sel_hi:[1,0]
	v_pk_mul_f32 v[12:13], v[12:13], v[238:239] op_sel_hi:[1,0]
	v_pk_mul_f32 v[10:11], v[10:11], v[238:239] op_sel_hi:[1,0]
	v_pk_mul_f32 v[8:9], v[8:9], v[238:239] op_sel_hi:[1,0]
	v_pk_mul_f32 v[6:7], v[6:7], v[238:239] op_sel_hi:[1,0]
	v_pk_mul_f32 v[4:5], v[4:5], v[238:239] op_sel_hi:[1,0]
	v_pk_mul_f32 v[2:3], v[2:3], v[238:239] op_sel_hi:[1,0]
	v_pk_mul_f32 v[0:1], v[0:1], v[238:239] op_sel_hi:[1,0]
	v_mul_f32_e32 v201, v201, v238
	s_branch .LBB0_287
